# v14 + attn_merge loop: next item's six loads issued one iteration ahead
# baseline (speedup 1.0000x reference)
.LBB0_643:
	s_or_b64 exec, exec, s[0:1]
	s_waitcnt lgkmcnt(0)
	s_barrier
	s_mov_b64 s[0:1], exec
	v_readlane_b32 s2, v246, 28
	v_readlane_b32 s3, v246, 29
	s_and_b64 s[2:3], s[0:1], s[2:3]
	s_mov_b64 exec, s[2:3]
	s_cbranch_execz .LBB0_646
	v_readlane_b32 s2, v247, 0
	v_readlane_b32 s4, v247, 2
	v_lshlrev_b32_e32 v0, 3, v130
	v_readlane_b32 s3, v247, 1
	v_readlane_b32 s5, v247, 3
	v_readlane_b32 s6, v247, 4
	v_readlane_b32 s10, v247, 8
	s_waitcnt vmcnt(5)
	v_lshl_add_u32 v4, s2, 11, v0
	s_lshl_b32 s6, s10, 11
	s_mov_b64 s[2:3], 0
	v_mov_b32_e32 v1, 0
	s_mov_b64 s[4:5], 0xfffff
	v_mov_b64_e32 v[2:3], v[134:135]
	v_readlane_b32 s7, v247, 5
	v_readlane_b32 s8, v247, 6
	v_readlane_b32 s9, v247, 7
	v_readlane_b32 s11, v247, 9
	v_lshrrev_b32_e32 v100, 5, v2
	v_mov_b32_e32 v101, 0
	v_lshrrev_b32_e32 v102, 4, v4
	v_lshl_add_u64 v[104:105], v[100:101], 4, s[52:53]
	v_and_b32_e32 v102, 12, v102
	v_mov_b32_e32 v103, 0
	v_lshl_add_u64 v[104:105], v[104:105], 0, v[102:103]
	v_mul_hi_i32_i24_e32 v107, 0x1200, v100
	v_mul_i32_i24_e32 v106, 0x1200, v100
	v_and_b32_e32 v102, 0xf8, v4
	v_lshl_add_u64 v[106:107], s[74:75], 0, v[106:107]
	v_lshlrev_b32_e32 v102, 1, v102
	global_load_dword v85, v[104:105], off
	s_mov_b64 s[8:9], 0x80000
	v_lshl_add_u64 v[106:107], v[106:107], 0, v[102:103]
	v_lshl_add_u64 v[108:109], v[104:105], 0, s[8:9]
	s_mov_b64 s[8:9], 0x100000
	global_load_dwordx4 v[88:91], v[106:107], off
	global_load_dwordx4 v[92:95], v[106:107], off offset:512
	v_lshl_add_u64 v[110:111], v[104:105], 0, s[8:9]
	global_load_dword v86, v[108:109], off
	global_load_dword v87, v[110:111], off
	global_load_dwordx4 v[96:99], v[106:107], off offset:1024
	s_waitcnt vmcnt(0)
.LBB0_645:
	v_lshrrev_b64 v[18:19], 5, v[2:3]
	v_and_b32_e32 v5, 0xf8, v4
	v_lshlrev_b32_e32 v0, 1, v5
	v_lshlrev_b64 v[18:19], 9, v[18:19]
	v_lshl_add_u64 v[18:19], s[72:73], 0, v[18:19]
	v_lshl_add_u64 v[18:19], v[18:19], 0, v[0:1]
	v_lshl_add_u64 v[2:3], v[2:3], 0, s[66:67]
	v_cmp_lt_u64_e32 vcc, s[4:5], v[2:3]
	s_nop 1
	s_or_b64 s[2:3], vcc, s[2:3]
	v_add_u32_e32 v4, s6, v4
	s_waitcnt vmcnt(1)
	v_mov_b32_e32 v5, v85
	v_mov_b32_e32 v34, v86
	v_mov_b32_e32 v35, v87
	v_mov_b32_e32 v6, v88
	v_mov_b32_e32 v7, v89
	v_mov_b32_e32 v8, v90
	v_mov_b32_e32 v9, v91
	v_mov_b32_e32 v10, v92
	v_mov_b32_e32 v11, v93
	v_mov_b32_e32 v12, v94
	v_mov_b32_e32 v13, v95
	v_mov_b32_e32 v14, v96
	v_mov_b32_e32 v15, v97
	v_mov_b32_e32 v16, v98
	v_mov_b32_e32 v17, v99
	v_min_u32_e32 v112, 0xfffff, v2
	v_lshlrev_b32_e32 v113, 3, v112
	v_lshrrev_b32_e32 v100, 5, v112
	v_mov_b32_e32 v101, 0
	v_lshrrev_b32_e32 v102, 4, v113
	v_lshl_add_u64 v[104:105], v[100:101], 4, s[52:53]
	v_and_b32_e32 v102, 12, v102
	v_mov_b32_e32 v103, 0
	v_lshl_add_u64 v[104:105], v[104:105], 0, v[102:103]
	v_mul_hi_i32_i24_e32 v107, 0x1200, v100
	v_mul_i32_i24_e32 v106, 0x1200, v100
	v_and_b32_e32 v102, 0xf8, v113
	v_lshl_add_u64 v[106:107], s[74:75], 0, v[106:107]
	v_lshlrev_b32_e32 v102, 1, v102
	global_load_dword v85, v[104:105], off
	s_mov_b64 s[8:9], 0x80000
	v_lshl_add_u64 v[106:107], v[106:107], 0, v[102:103]
	v_lshl_add_u64 v[108:109], v[104:105], 0, s[8:9]
	s_mov_b64 s[8:9], 0x100000
	global_load_dwordx4 v[88:91], v[106:107], off
	global_load_dwordx4 v[92:95], v[106:107], off offset:512
	v_lshl_add_u64 v[110:111], v[104:105], 0, s[8:9]
	global_load_dword v86, v[108:109], off
	global_load_dword v87, v[110:111], off
	global_load_dwordx4 v[96:99], v[106:107], off offset:1024
	v_and_b32_e32 v25, 0xffff0000, v6
	v_max3_f32 v0, v5, v34, v35
	v_lshlrev_b32_e32 v24, 16, v10
	v_and_b32_e32 v27, 0xffff0000, v10
	v_lshlrev_b32_e32 v10, 16, v12
	v_and_b32_e32 v31, 0xffff0000, v12
	v_sub_f32_e32 v5, v5, v0
	v_sub_f32_e32 v12, v34, v0
	v_sub_f32_e32 v0, v35, v0
	v_mul_f32_e32 v5, 0x3fb8aa3b, v5
	v_mul_f32_e32 v12, 0x3fb8aa3b, v12
	v_lshlrev_b32_e32 v26, 16, v6
	v_lshlrev_b32_e32 v28, 16, v11
	v_and_b32_e32 v29, 0xffff0000, v7
	v_lshlrev_b32_e32 v6, 16, v7
	v_and_b32_e32 v7, 0xffff0000, v11
	v_and_b32_e32 v11, 0xffff0000, v8
	v_lshlrev_b32_e32 v30, 16, v8
	v_lshlrev_b32_e32 v32, 16, v13
	v_and_b32_e32 v33, 0xffff0000, v9
	v_lshlrev_b32_e32 v8, 16, v9
	v_and_b32_e32 v9, 0xffff0000, v13
	v_mul_f32_e32 v0, 0x3fb8aa3b, v0
	v_exp_f32_e32 v13, v5
	v_exp_f32_e32 v12, v12
	v_exp_f32_e32 v5, v0
	v_lshlrev_b32_e32 v20, 16, v14
	v_and_b32_e32 v21, 0xffff0000, v14
	v_add_f32_e32 v0, v13, v12
	v_add_f32_e32 v0, v5, v0
	v_div_scale_f32 v34, s[8:9], v0, v0, 1.0
	v_rcp_f32_e32 v36, v34
	v_div_scale_f32 v35, vcc, 1.0, v0, 1.0
	v_lshlrev_b32_e32 v14, 16, v15
	v_fma_f32 v37, -v34, v36, 1.0
	v_fmac_f32_e32 v36, v37, v36
	v_mul_f32_e32 v37, v35, v36
	v_fma_f32 v38, -v34, v37, v35
	v_fmac_f32_e32 v37, v38, v36
	v_fma_f32 v34, -v34, v37, v35
	v_div_fmas_f32 v34, v34, v36, v37
	v_div_fixup_f32 v0, v34, v0, 1.0
	v_pk_mul_f32 v[12:13], v[12:13], v[0:1] op_sel_hi:[1,0]
	v_and_b32_e32 v15, 0xffff0000, v15
	v_pk_mul_f32 v[26:27], v[12:13], v[26:27] op_sel:[1,0] op_sel_hi:[0,1]
	v_pk_mul_f32 v[6:7], v[12:13], v[6:7] op_sel:[1,0] op_sel_hi:[0,1]
	v_pk_mul_f32 v[30:31], v[12:13], v[30:31] op_sel:[1,0] op_sel_hi:[0,1]
	v_pk_mul_f32 v[8:9], v[12:13], v[8:9] op_sel:[1,0] op_sel_hi:[0,1]
	v_lshlrev_b32_e32 v22, 16, v16
	v_and_b32_e32 v23, 0xffff0000, v16
	v_lshlrev_b32_e32 v16, 16, v17
	v_and_b32_e32 v17, 0xffff0000, v17
	v_mul_f32_e32 v34, v5, v0
	v_pk_fma_f32 v[24:25], v[12:13], v[24:25], v[26:27]
	v_pk_fma_f32 v[6:7], v[12:13], v[28:29], v[6:7]
	v_pk_fma_f32 v[10:11], v[12:13], v[10:11], v[30:31]
	v_pk_fma_f32 v[8:9], v[12:13], v[32:33], v[8:9]
	v_pk_fma_f32 v[12:13], v[34:35], v[20:21], v[24:25] op_sel_hi:[0,1,1]
	v_pk_fma_f32 v[14:15], v[34:35], v[14:15], v[6:7] op_sel_hi:[0,1,1]
	v_pk_fma_f32 v[10:11], v[34:35], v[22:23], v[10:11] op_sel_hi:[0,1,1]
	v_pk_fma_f32 v[16:17], v[34:35], v[16:17], v[8:9] op_sel_hi:[0,1,1]
	v_cvt_pk_bf16_f32 v6, v12, v13
	v_cvt_pk_bf16_f32 v7, v14, v15
	v_cvt_pk_bf16_f32 v8, v10, v11
	v_cvt_pk_bf16_f32 v9, v16, v17
	global_store_dwordx4 v[18:19], v[6:9], off
	s_andn2_b64 exec, exec, s[2:3]
	s_cbranch_execnz .LBB0_645
